# up-projection K-loop: LDS-DMA loads in scalar-base + 32-bit offset form (no 64-bit VALU address adds in the load sections)
# baseline (speedup 1.0000x reference)
.LBB0_363:
	s_add_u32 s34, s30, 0xfffc0080
	s_addc_u32 s35, s31, -1
	s_add_i32 s57, 0, 0x10000
	s_cmp_eq_u32 s56, 12
	s_cselect_b32 s37, s23, s35
	s_cselect_b32 s36, s39, s34
	v_add_u32_e32 v146, s57, v155
	s_cselect_b32 s35, s21, s43
	s_cselect_b32 s34, s40, s41
	s_add_i32 s60, 0, 0x14000
	ds_read_b128 v[142:145], v146
	ds_read_b128 v[168:171], v146 offset:1024
	ds_read_b128 v[172:175], v146 offset:2048
	ds_read_b128 v[176:179], v146 offset:3072
	v_add_u32_e32 v146, s60, v155
	ds_read_b128 v[180:183], v146
	ds_read_b128 v[184:187], v146 offset:1024
	ds_read_b128 v[188:191], v146 offset:2048
	ds_read_b128 v[192:195], v146 offset:3072
	s_add_i32 m0, s48, 0xc000
	ds_read_b128 v[196:199], v157
	ds_read_b128 v[200:203], v157 offset:1024
	ds_read_b128 v[204:207], v157 offset:2048
	ds_read_b128 v[220:223], v157 offset:3072
	ds_read_b128 v[236:239], v157 offset:4096
	ds_read_b128 v[240:243], v157 offset:5120
	ds_read_b128 v[244:247], v157 offset:6144
	ds_read_b128 v[248:251], v157 offset:7168
	global_load_lds_dwordx4 v140, s[30:31]
	s_add_i32 m0, s48, 0xe000
	s_nop 0
	global_load_lds_dwordx4 v138, s[30:31]
	s_branch .Lpadj_12
	s_nop 0
	s_nop 0
	s_nop 0
	s_nop 0
	s_nop 0
	s_nop 0
	s_nop 0
	s_nop 0
	s_nop 0
	s_nop 0
	s_nop 0
	s_nop 0
.Lpadj_12:
	s_waitcnt vmcnt(8)
	s_waitcnt lgkmcnt(0)
	s_barrier
	v_mfma_f32_16x16x32_bf16 v[126:129], v[142:145], v[196:199], v[126:129]
	v_mfma_f32_16x16x32_bf16 v[118:121], v[172:175], v[196:199], v[118:121]
	v_mfma_f32_16x16x32_bf16 v[110:113], v[142:145], v[204:207], v[110:113]
	v_mfma_f32_16x16x32_bf16 v[102:105], v[172:175], v[204:207], v[102:105]
	v_mfma_f32_16x16x32_bf16 v[94:97], v[142:145], v[236:239], v[94:97]
	v_mfma_f32_16x16x32_bf16 v[86:89], v[172:175], v[236:239], v[86:89]
	v_mfma_f32_16x16x32_bf16 v[78:81], v[142:145], v[244:247], v[78:81]
	v_mfma_f32_16x16x32_bf16 v[70:73], v[172:175], v[244:247], v[70:73]
	v_mfma_f32_16x16x32_bf16 v[126:129], v[168:171], v[200:203], v[126:129]
	v_mfma_f32_16x16x32_bf16 v[118:121], v[176:179], v[200:203], v[118:121]
	v_mfma_f32_16x16x32_bf16 v[110:113], v[168:171], v[220:223], v[110:113]
	v_mfma_f32_16x16x32_bf16 v[102:105], v[176:179], v[220:223], v[102:105]
	v_mfma_f32_16x16x32_bf16 v[94:97], v[168:171], v[240:243], v[94:97]
	v_mfma_f32_16x16x32_bf16 v[86:89], v[176:179], v[240:243], v[86:89]
	v_mfma_f32_16x16x32_bf16 v[78:81], v[168:171], v[248:251], v[78:81]
	v_mfma_f32_16x16x32_bf16 v[70:73], v[176:179], v[248:251], v[70:73]
	v_mfma_f32_16x16x32_bf16 v[122:125], v[180:183], v[196:199], v[122:125]
	v_mfma_f32_16x16x32_bf16 v[114:117], v[188:191], v[196:199], v[114:117]
	v_mfma_f32_16x16x32_bf16 v[106:109], v[180:183], v[204:207], v[106:109]
	v_mfma_f32_16x16x32_bf16 v[98:101], v[188:191], v[204:207], v[98:101]
	v_mfma_f32_16x16x32_bf16 v[90:93], v[180:183], v[236:239], v[90:93]
	v_mfma_f32_16x16x32_bf16 v[82:85], v[188:191], v[236:239], v[82:85]
	v_mfma_f32_16x16x32_bf16 v[74:77], v[180:183], v[244:247], v[74:77]
	v_mfma_f32_16x16x32_bf16 v[66:69], v[188:191], v[244:247], v[66:69]
	v_mfma_f32_16x16x32_bf16 v[122:125], v[184:187], v[200:203], v[122:125]
	v_mfma_f32_16x16x32_bf16 v[114:117], v[192:195], v[200:203], v[114:117]
	v_mfma_f32_16x16x32_bf16 v[106:109], v[184:187], v[220:223], v[106:109]
	v_mfma_f32_16x16x32_bf16 v[98:101], v[192:195], v[220:223], v[98:101]
	v_mfma_f32_16x16x32_bf16 v[90:93], v[184:187], v[240:243], v[90:93]
	v_mfma_f32_16x16x32_bf16 v[82:85], v[192:195], v[240:243], v[82:85]
	v_mfma_f32_16x16x32_bf16 v[74:77], v[184:187], v[248:251], v[74:77]
	v_mfma_f32_16x16x32_bf16 v[66:69], v[192:195], v[248:251], v[66:69]
	s_barrier
	s_add_i32 s57, s57, s44
	s_mov_b32 m0, s57
	ds_read_b128 v[196:199], v157 offset:16384
	ds_read_b128 v[200:203], v157 offset:17408
	ds_read_b128 v[204:207], v157 offset:18432
	ds_read_b128 v[220:223], v157 offset:19456
	ds_read_b128 v[236:239], v157 offset:20480
	ds_read_b128 v[240:243], v157 offset:21504
	ds_read_b128 v[244:247], v157 offset:22528
	ds_read_b128 v[248:251], v157 offset:23552
	global_load_lds_dwordx4 v134, s[34:35]
	s_add_i32 m0, s57, 0x2000
	s_add_u32 s58, s34, 0x40000
	s_addc_u32 s59, s35, 0
	s_add_i32 s57, s60, s44
	global_load_lds_dwordx4 v130, s[34:35]
	s_mov_b32 m0, s57
	s_nop 0
	global_load_lds_dwordx4 v134, s[58:59]
	s_add_i32 m0, s57, 0x2000
	s_nop 0
	global_load_lds_dwordx4 v130, s[58:59]
	s_mov_b32 m0, s48
	s_nop 0
	global_load_lds_dwordx4 v136, s[36:37]
	s_mov_b32 m0, s49
	s_nop 0
	global_load_lds_dwordx4 v132, s[36:37]
	s_branch .Lpadj_13
	s_nop 0
	s_nop 0
	s_nop 0
	s_nop 0
	s_nop 0
	s_nop 0
	s_nop 0
	s_nop 0
	s_nop 0
	s_nop 0
	s_nop 0
	s_nop 0
	s_nop 0
	s_nop 0
.Lpadj_13:
	s_waitcnt vmcnt(8)
	s_waitcnt lgkmcnt(0)
	s_barrier
	v_mfma_f32_16x16x32_bf16 v[62:65], v[142:145], v[196:199], v[62:65]
	v_mfma_f32_16x16x32_bf16 v[54:57], v[172:175], v[196:199], v[54:57]
	v_mfma_f32_16x16x32_bf16 v[46:49], v[142:145], v[204:207], v[46:49]
	v_mfma_f32_16x16x32_bf16 v[38:41], v[172:175], v[204:207], v[38:41]
	v_mfma_f32_16x16x32_bf16 v[30:33], v[142:145], v[236:239], v[30:33]
	v_mfma_f32_16x16x32_bf16 v[22:25], v[172:175], v[236:239], v[22:25]
	v_mfma_f32_16x16x32_bf16 v[14:17], v[142:145], v[244:247], v[14:17]
	v_mfma_f32_16x16x32_bf16 v[6:9], v[172:175], v[244:247], v[6:9]
	v_mfma_f32_16x16x32_bf16 v[62:65], v[168:171], v[200:203], v[62:65]
	v_mfma_f32_16x16x32_bf16 v[54:57], v[176:179], v[200:203], v[54:57]
	v_mfma_f32_16x16x32_bf16 v[46:49], v[168:171], v[220:223], v[46:49]
	v_mfma_f32_16x16x32_bf16 v[38:41], v[176:179], v[220:223], v[38:41]
	v_mfma_f32_16x16x32_bf16 v[30:33], v[168:171], v[240:243], v[30:33]
	v_mfma_f32_16x16x32_bf16 v[22:25], v[176:179], v[240:243], v[22:25]
	v_mfma_f32_16x16x32_bf16 v[14:17], v[168:171], v[248:251], v[14:17]
	v_mfma_f32_16x16x32_bf16 v[6:9], v[176:179], v[248:251], v[6:9]
	v_mfma_f32_16x16x32_bf16 v[58:61], v[180:183], v[196:199], v[58:61]
	v_mfma_f32_16x16x32_bf16 v[50:53], v[188:191], v[196:199], v[50:53]
	v_mfma_f32_16x16x32_bf16 v[42:45], v[180:183], v[204:207], v[42:45]
	v_mfma_f32_16x16x32_bf16 v[34:37], v[188:191], v[204:207], v[34:37]
	v_mfma_f32_16x16x32_bf16 v[26:29], v[180:183], v[236:239], v[26:29]
	v_mfma_f32_16x16x32_bf16 v[18:21], v[188:191], v[236:239], v[18:21]
	v_mfma_f32_16x16x32_bf16 v[10:13], v[180:183], v[244:247], v[10:13]
	v_mfma_f32_16x16x32_bf16 v[2:5], v[188:191], v[244:247], v[2:5]
	v_mfma_f32_16x16x32_bf16 v[58:61], v[184:187], v[200:203], v[58:61]
	v_mfma_f32_16x16x32_bf16 v[50:53], v[192:195], v[200:203], v[50:53]
	v_mfma_f32_16x16x32_bf16 v[42:45], v[184:187], v[220:223], v[42:45]
	v_mfma_f32_16x16x32_bf16 v[34:37], v[192:195], v[220:223], v[34:37]
	v_mfma_f32_16x16x32_bf16 v[26:29], v[184:187], v[240:243], v[26:29]
	v_mfma_f32_16x16x32_bf16 v[18:21], v[192:195], v[240:243], v[18:21]
	v_mfma_f32_16x16x32_bf16 v[10:13], v[184:187], v[248:251], v[10:13]
	v_mfma_f32_16x16x32_bf16 v[2:5], v[192:195], v[248:251], v[2:5]
	s_barrier
	s_add_i32 s57, 0, 0x18000
	v_add_u32_e32 v164, s57, v155
	s_add_i32 s58, 0, 0x1c000
	ds_read_b128 v[142:145], v164
	ds_read_b128 v[168:171], v164 offset:1024
	ds_read_b128 v[172:175], v164 offset:2048
	ds_read_b128 v[176:179], v164 offset:3072
	v_add_u32_e32 v164, s58, v155
	ds_read_b128 v[180:183], v164
	ds_read_b128 v[184:187], v164 offset:1024
	ds_read_b128 v[188:191], v164 offset:2048
	ds_read_b128 v[192:195], v164 offset:3072
	s_add_u32 s36, s36, 0x40000
	s_addc_u32 s37, s37, 0
	s_mov_b32 m0, s50
	ds_read_b128 v[196:199], v157 offset:32768
	ds_read_b128 v[200:203], v157 offset:33792
	ds_read_b128 v[204:207], v157 offset:34816
	ds_read_b128 v[220:223], v157 offset:35840
	ds_read_b128 v[236:239], v157 offset:36864
	ds_read_b128 v[240:243], v157 offset:37888
	ds_read_b128 v[244:247], v157 offset:38912
	ds_read_b128 v[248:251], v157 offset:39936
	global_load_lds_dwordx4 v136, s[36:37]
	s_mov_b32 m0, s51
	s_nop 0
	global_load_lds_dwordx4 v132, s[36:37]
	s_branch .Lpadj_14
	s_nop 0
	s_nop 0
	s_nop 0
	s_nop 0
	s_nop 0
	s_nop 0
	s_nop 0
	s_nop 0
	s_nop 0
	s_nop 0
	s_nop 0
.Lpadj_14:
	s_waitcnt vmcnt(8)
	s_waitcnt lgkmcnt(0)
	s_barrier
	v_mfma_f32_16x16x32_bf16 v[126:129], v[142:145], v[196:199], v[126:129]
	v_mfma_f32_16x16x32_bf16 v[118:121], v[172:175], v[196:199], v[118:121]
	v_mfma_f32_16x16x32_bf16 v[110:113], v[142:145], v[204:207], v[110:113]
	v_mfma_f32_16x16x32_bf16 v[102:105], v[172:175], v[204:207], v[102:105]
	v_mfma_f32_16x16x32_bf16 v[94:97], v[142:145], v[236:239], v[94:97]
	v_mfma_f32_16x16x32_bf16 v[86:89], v[172:175], v[236:239], v[86:89]
	v_mfma_f32_16x16x32_bf16 v[78:81], v[142:145], v[244:247], v[78:81]
	v_mfma_f32_16x16x32_bf16 v[70:73], v[172:175], v[244:247], v[70:73]
	v_mfma_f32_16x16x32_bf16 v[126:129], v[168:171], v[200:203], v[126:129]
	v_mfma_f32_16x16x32_bf16 v[118:121], v[176:179], v[200:203], v[118:121]
	v_mfma_f32_16x16x32_bf16 v[110:113], v[168:171], v[220:223], v[110:113]
	v_mfma_f32_16x16x32_bf16 v[102:105], v[176:179], v[220:223], v[102:105]
	v_mfma_f32_16x16x32_bf16 v[94:97], v[168:171], v[240:243], v[94:97]
	v_mfma_f32_16x16x32_bf16 v[86:89], v[176:179], v[240:243], v[86:89]
	v_mfma_f32_16x16x32_bf16 v[78:81], v[168:171], v[248:251], v[78:81]
	v_mfma_f32_16x16x32_bf16 v[70:73], v[176:179], v[248:251], v[70:73]
	v_mfma_f32_16x16x32_bf16 v[122:125], v[180:183], v[196:199], v[122:125]
	v_mfma_f32_16x16x32_bf16 v[114:117], v[188:191], v[196:199], v[114:117]
	v_mfma_f32_16x16x32_bf16 v[106:109], v[180:183], v[204:207], v[106:109]
	v_mfma_f32_16x16x32_bf16 v[98:101], v[188:191], v[204:207], v[98:101]
	v_mfma_f32_16x16x32_bf16 v[90:93], v[180:183], v[236:239], v[90:93]
	v_mfma_f32_16x16x32_bf16 v[82:85], v[188:191], v[236:239], v[82:85]
	v_mfma_f32_16x16x32_bf16 v[74:77], v[180:183], v[244:247], v[74:77]
	v_mfma_f32_16x16x32_bf16 v[66:69], v[188:191], v[244:247], v[66:69]
	v_mfma_f32_16x16x32_bf16 v[122:125], v[184:187], v[200:203], v[122:125]
	v_mfma_f32_16x16x32_bf16 v[114:117], v[192:195], v[200:203], v[114:117]
	v_mfma_f32_16x16x32_bf16 v[106:109], v[184:187], v[220:223], v[106:109]
	v_mfma_f32_16x16x32_bf16 v[98:101], v[192:195], v[220:223], v[98:101]
	v_mfma_f32_16x16x32_bf16 v[90:93], v[184:187], v[240:243], v[90:93]
	v_mfma_f32_16x16x32_bf16 v[82:85], v[192:195], v[240:243], v[82:85]
	v_mfma_f32_16x16x32_bf16 v[74:77], v[184:187], v[248:251], v[74:77]
	v_mfma_f32_16x16x32_bf16 v[66:69], v[192:195], v[248:251], v[66:69]
	s_barrier
	s_add_u32 s100, s36, 0xfffc0080
	s_addc_u32 s101, s37, -1
	s_add_i32 s36, s57, s44
	s_add_u32 s34, s34, 0x80
	s_mov_b32 m0, s36
	s_addc_u32 s35, s35, 0
	ds_read_b128 v[196:199], v157 offset:49152
	ds_read_b128 v[200:203], v157 offset:50176
	ds_read_b128 v[204:207], v157 offset:51200
	ds_read_b128 v[220:223], v157 offset:52224
	ds_read_b128 v[236:239], v157 offset:53248
	ds_read_b128 v[240:243], v157 offset:54272
	ds_read_b128 v[244:247], v157 offset:55296
	ds_read_b128 v[248:251], v157 offset:56320
	global_load_lds_dwordx4 v134, s[34:35]
	s_add_i32 m0, s36, 0x2000
	s_add_i32 s36, s58, s44
	global_load_lds_dwordx4 v130, s[34:35]
	s_mov_b32 m0, s36
	s_add_u32 s34, s34, 0x40000
	s_addc_u32 s35, s35, 0
	global_load_lds_dwordx4 v134, s[34:35]
	s_add_i32 m0, s36, 0x2000
	s_nop 0
	global_load_lds_dwordx4 v130, s[34:35]
	s_mov_b32 m0, s52
	s_nop 0
	global_load_lds_dwordx4 v136, s[100:101]
	s_mov_b32 m0, s53
	s_nop 0
	global_load_lds_dwordx4 v132, s[100:101]
	s_branch .Lpadj_15
	s_nop 0
	s_nop 0
	s_nop 0
	s_nop 0
	s_nop 0
	s_nop 0
	s_nop 0
	s_nop 0
	s_nop 0
